# NA attention: static s_setprio 1 for waves 0-3 (older half) instead
# speedup vs baseline: 1.0085x; 1.0011x over previous
; __device__ __forceinline__ int opaque_tid() { int t = threadIdx.x; asm volatile("" : "+v"(t)); return t; }
; __device__ __forceinline__ void na_unit3(char* lds, const bf16_t* __restrict__ Qp, const bf16_t* __restrict__ Knp, const bf16_t* __restrict__ Vp, ...
;     ...
;   const int tid = opaque_tid(), wid = __builtin_amdgcn_readfirstlane(tid >> 6), lane = tid & 63, r32 = lane & 31, hi = lane >> 5;
.LBB0_276:
	v_readfirstlane_b32 s100, v252
	s_lshr_b32 s100, s100, 8
	s_cmp_lg_u32 s100, 0
	s_cbranch_scc1 .Lna_prio_skip
	s_setprio 1
